# chain v2b + blocked K/V attention, +8 bytes of padding after the attention loop (same loop-head byte phases as the previous best)
# speedup vs baseline: 1.0110x; 1.0110x over previous
.Lat_pv_done:
	s_nop 7
	v_cvt_pk_bf16_f32 v22, v240, v240
	v_cvt_pk_bf16_f32 v23, v241, v241
	v_cvt_pk_bf16_f32 v24, v242, v242
	v_cvt_pk_bf16_f32 v25, v243, v243
	v_cvt_pk_bf16_f32 v26, v244, v244
	v_cvt_pk_bf16_f32 v27, v245, v245
	v_cvt_pk_bf16_f32 v28, v246, v246
	v_cvt_pk_bf16_f32 v29, v247, v247
	v_cvt_pk_bf16_f32 v134, v248, v248
	v_cvt_pk_bf16_f32 v135, v249, v249
	v_cvt_pk_bf16_f32 v136, v250, v250
	v_cvt_pk_bf16_f32 v137, v251, v251
	v_cvt_pk_bf16_f32 v138, v120, v120
	v_cvt_pk_bf16_f32 v139, v121, v121
	v_cvt_pk_bf16_f32 v150, v122, v122
	v_cvt_pk_bf16_f32 v151, v123, v123
	global_store_short v17, v22, s[20:21]
	global_store_short v17, v23, s[20:21] offset:2048
	global_store_short v18, v24, s[20:21]
	global_store_short v18, v25, s[20:21] offset:2048
	global_store_short v17, v26, s[20:21] offset:32
	global_store_short v17, v27, s[20:21] offset:2080
	global_store_short v18, v28, s[20:21] offset:32
	global_store_short v18, v29, s[20:21] offset:2080
	global_store_short v17, v134, s[20:21] offset:64
	global_store_short v17, v135, s[20:21] offset:2112
	global_store_short v18, v136, s[20:21] offset:64
	global_store_short v18, v137, s[20:21] offset:2112
	global_store_short v17, v138, s[20:21] offset:96
	global_store_short v17, v139, s[20:21] offset:2144
	global_store_short v18, v150, s[20:21] offset:96
	global_store_short v18, v151, s[20:21] offset:2144
	s_add_u32 s3, s3, s6
	s_cmp_lt_u32 s3, 0x2000
	s_cbranch_scc1 .Lat_loop
	v_and_b32_e32 v10, 15, v0
	s_add_u32 s74, s0, 0xd8
	s_addc_u32 s75, s1, 0
	v_mov_b64_e32 v[2:3], s[74:75]
	s_mov_b64 s[64:65], exec
	s_nop 0
	s_nop 0
